# sample output tiles assigned to the 64 workgroups that form 8 complete row panels (instead of 2 per panel)
# speedup vs baseline: 1.0012x; 1.0012x over previous
.LBB0_624:
	s_or_b64 exec, exec, s[4:5]
	v_readlane_b32 s34, v238, 15
	s_mov_b32 s32, s2
	s_and_b32 s0, s2, 7
	s_cmp_gt_u32 s0, 1
	v_readlane_b32 s35, v238, 16
	s_waitcnt lgkmcnt(0)
	s_barrier
	s_cbranch_scc1 .LBB0_648
	s_lshr_b32 s0, s2, 3
	s_lshl_b32 s0, s0, 1
	s_and_b32 s1, s2, 7
	s_add_i32 s2, s0, s1
	v_mbcnt_lo_u32_b32 v23, -1, 0
	v_mbcnt_hi_u32_b32 v23, -1, v23
	s_lshl_b32 s4, s2, 5
	v_add_u32_e32 v22, s97, v23
	v_ashrrev_i32_e32 v24, 6, v22
	v_and_b32_e32 v25, 15, v23
	v_lshlrev_b32_e32 v0, 8, v24
	v_or_b32_e32 v2, s4, v25
	v_ashrrev_i32_e32 v1, 31, v0
	v_ashrrev_i32_e32 v3, 31, v2
	v_lshlrev_b64 v[2:3], 12, v[2:3]
	v_lshlrev_b64 v[16:17], 1, v[0:1]
	v_and_b32_e32 v0, 48, v23
	v_or_b32_e32 v2, v2, v0
	v_lshl_or_b32 v0, v25, 12, v0
	v_mov_b32_e32 v1, 0
	v_lshl_add_u64 v[18:19], s[92:93], 0, v[2:3]
	v_lshl_add_u64 v[20:21], s[92:93], 0, v[0:1]
	s_movk_i32 s5, 0xffe0
	s_mov_b32 s6, 0xc800000
	s_mov_b32 s7, 0xc810000
	s_mov_b32 s8, 0x1a00000
	s_mov_b32 s9, 0x1a10000
	s_mov_b64 s[0:1], 0x100
	v_mov_b32_e32 v0, v1
	v_mov_b32_e32 v2, v1
	v_mov_b32_e32 v3, v1
	v_mov_b32_e32 v8, v1
	v_mov_b32_e32 v9, v1
	v_mov_b32_e32 v10, v1
	v_mov_b32_e32 v11, v1
	v_mov_b32_e32 v4, v1
	v_mov_b32_e32 v5, v1
	v_mov_b32_e32 v6, v1
	v_mov_b32_e32 v7, v1
	v_mov_b32_e32 v12, v1
	v_mov_b32_e32 v13, v1
	v_mov_b32_e32 v14, v1
	v_mov_b32_e32 v15, v1

.LBB0_648:
	s_mov_b32 s2, s32
	v_mbcnt_lo_u32_b32 v0, -1, 0
	v_mbcnt_hi_u32_b32 v0, -1, v0
	s_cmpk_gt_i32 s2, 0xff
	v_add_u32_e32 v144, s97, v0
	s_nop 0
	v_readfirstlane_b32 s28, v144
	s_cbranch_scc1 .LBB0_700
	v_lshlrev_b32_e32 v0, 4, v144
	v_add_u32_e32 v1, 0x2000, v0
	v_ashrrev_i32_e32 v2, 31, v1
	v_lshrrev_b32_e32 v2, 22, v2
	v_add_u32_e32 v2, v1, v2
	v_ashrrev_i32_e32 v8, 10, v2
	v_mul_i32_i24_e32 v3, 0x400, v8
	v_sub_u32_e32 v1, v1, v3
	v_lshrrev_b32_e32 v3, 4, v1
	v_bitop3_b32 v1, v3, v1, 32 bitop3:0x6c
	v_ashrrev_i32_e32 v3, 31, v1
	v_lshrrev_b32_e32 v3, 26, v3
	v_add_u32_e32 v3, v1, v3
	v_ashrrev_i32_e32 v9, 6, v3
	v_and_b32_e32 v3, 0xc0, v3
	v_sub_u32_e32 v1, v1, v3
	v_mov_b32_e32 v3, 1
	v_lshlrev_b32_e32 v2, 5, v8
	v_ashrrev_i16_sdwa v1, v3, sext(v1) dst_sel:DWORD dst_unused:UNUSED_PAD src0_sel:DWORD src1_sel:BYTE_0
	s_ashr_i32 s4, s28, 6
	v_readlane_b32 s5, v239, 49
	v_and_b32_e32 v2, 32, v2
	v_bfe_i32 v10, v1, 0, 16
	v_readlane_b32 s6, v239, 50
	s_ashr_i32 s1, s28, 8
	s_lshl_b32 s9, s4, 10
	s_lshl_b32 s0, s5, 5
	v_add_u32_e32 v1, v2, v10
	v_lshlrev_b32_e32 v2, 3, v8
	v_readlane_b32 s7, v239, 51
	s_mul_i32 s5, s5, 33
	v_and_b32_e32 v2, 0xffff0, v2
	s_and_b64 s[6:7], s[6:7], exec
	v_add_lshl_u32 v2, v9, v2, 12
	s_cselect_b32 s0, s5, s0
	v_readlane_b32 s5, v239, 52
	v_lshl_add_u32 v128, v1, 1, v2
	v_bfe_i32 v2, v144, 27, 1
	s_add_i32 s0, s0, s5
	v_lshrrev_b32_e32 v2, 22, v2
	s_ashr_i32 s5, s0, 31
	v_add_u32_e32 v2, v0, v2
	s_lshr_b32 s5, s5, 26
	v_and_b32_e32 v2, 0xfffffc00, v2
	s_add_i32 s5, s0, s5
	v_sub_u32_e32 v0, v0, v2
	s_ashr_i32 s6, s5, 6
	s_and_b32 s5, s5, 0xffc0
	v_lshrrev_b32_e32 v2, 4, v0
	s_sub_i32 s5, s0, s5
	v_bitop3_b32 v0, v2, v0, 32 bitop3:0x6c
	s_bfe_i32 s0, s5, 0x80000
	v_ashrrev_i32_e32 v2, 31, v0
	s_bfe_u32 s0, s0, 0x3000c
	v_ashrrev_i32_e32 v1, 31, v144
	v_lshrrev_b32_e32 v2, 26, v2
	s_add_i32 s7, s5, s0
	v_lshrrev_b32_e32 v1, 26, v1
	v_add_u32_e32 v2, v0, v2
	s_bfe_i32 s0, s7, 0x80000
	s_and_b32 s7, s7, 0xf8
	v_add_u32_e32 v1, v144, v1
	v_ashrrev_i32_e32 v12, 6, v2
	v_and_b32_e32 v2, 0xc0, v2
	s_sub_i32 s5, s5, s7
	v_ashrrev_i32_e32 v11, 6, v1
	v_sub_u32_e32 v0, v0, v2
	s_lshl_b32 s6, s6, 3
	s_sext_i32_i16 s0, s0
	s_sext_i32_i8 s5, s5
	v_lshlrev_b32_e32 v1, 5, v11
	v_ashrrev_i16_sdwa v0, v3, sext(v0) dst_sel:DWORD dst_unused:UNUSED_PAD src0_sel:DWORD src1_sel:BYTE_0
	s_lshr_b32 s0, s0, 3
	s_add_i32 s6, s6, s5
	v_and_b32_e32 v1, 32, v1
	v_bfe_i32 v13, v0, 0, 16
	s_ashr_i32 s7, s6, 31
	s_bfe_i64 s[12:13], s[0:1], 0x100000
	v_add_u32_e32 v0, v1, v13
	v_lshlrev_b32_e32 v1, 3, v11
	s_lshl_b64 s[10:11], s[6:7], 20
	s_lshl_b64 s[12:13], s[12:13], 20
	v_and_b32_e32 v1, 0xffff0, v1
	s_add_u32 s22, s34, s12
	v_add_lshl_u32 v1, v12, v1, 12
	s_addc_u32 s23, s35, s13
	s_add_i32 s29, s9, 0
	v_lshl_add_u32 v130, v0, 1, v1
	s_add_i32 m0, s29, 0x10000
	v_mov_b32_e32 v131, 0
	global_load_lds_dwordx4 v130, s[22:23]
	s_add_i32 m0, s29, 0x12000
	s_add_u32 s12, s22, 0x80000
	global_load_lds_dwordx4 v128, s[22:23]
	s_addc_u32 s13, s23, 0
	s_add_i32 m0, s29, 0x14000
	v_mov_b32_e32 v129, v131
	global_load_lds_dwordx4 v130, s[12:13]
	s_add_i32 m0, s29, 0x16000
	s_add_u32 s10, s30, s10
	s_addc_u32 s11, s31, s11
	s_add_i32 s33, s29, 0x2000
	global_load_lds_dwordx4 v128, s[12:13]
	s_mov_b32 m0, s29
	s_add_u32 s12, s10, 0x80000
	global_load_lds_dwordx4 v130, s[10:11]
	s_mov_b32 m0, s33
	s_addc_u32 s13, s11, 0
	s_add_i32 s36, s29, 0x4000
	global_load_lds_dwordx4 v128, s[10:11]
	s_mov_b32 m0, s36
	s_add_i32 s37, s29, 0x6000
	global_load_lds_dwordx4 v130, s[12:13]
	s_mov_b32 m0, s37
	v_lshl_add_u64 v[6:7], s[22:23], 0, v[130:131]
	global_load_lds_dwordx4 v128, s[12:13]
	v_lshl_add_u64 v[4:5], s[22:23], 0, v[128:129]
	v_lshl_add_u64 v[2:3], s[10:11], 0, v[130:131]
	s_cmp_lg_u32 s1, 1
	v_lshl_add_u64 v[0:1], s[10:11], 0, v[128:129]
	s_cbranch_scc1 .LBB0_651
	s_barrier
